# stick-breaking attention epilogue: 8 row-per-lane dwordx2 stores widened to 4 dwordx4 with v_permlane32_swap pairs (same bytes, same addresses)
# speedup vs baseline: 1.0006x; 1.0006x over previous
.LBB0_531:
	s_mulk_i32 s6, 0xb820
	s_add_i32 s2, s7, s6
	s_and_saveexec_b64 s[0:1], s[40:41]
	v_lshl_add_u32 v0, v180, 2, s2
	ds_write_b32 v0, v64 offset:36864
	s_or_b64 exec, exec, s[0:1]
	v_mov_b32_e32 v0, s2
	s_waitcnt lgkmcnt(0)
	s_barrier
	ds_read_b128 v[2:5], v0 offset:36864
	ds_read_b128 v[6:9], v0 offset:36880
	s_add_i32 s0, s5, -1
	s_cmp_lg_u32 s5, 0
	s_cselect_b64 s[2:3], -1, 0
	s_waitcnt lgkmcnt(1)
	v_and_b32_e32 v0, v2, v3
	v_and_b32_e32 v0, v0, v4
	v_and_b32_e32 v0, v0, v5
	s_waitcnt lgkmcnt(0)
	v_and_b32_e32 v0, v0, v6
	v_and_b32_e32 v0, v0, v7
	v_and_b32_e32 v0, v0, v8
	v_and_b32_e32 v0, v0, v9
	v_cmp_eq_u32_e32 vcc, 0, v0
	s_and_b64 s[2:3], s[2:3], vcc
	v_add_u32_e32 v186, 1, v186
	s_sub_i32 s54, s54, 64
	s_and_b64 vcc, exec, s[2:3]
	s_cbranch_vccnz .LBB0_517
	v_lshlrev_b64 v[2:3], 10, v[176:177]
	v_mov_b32_e32 v0, 1.0
	v_lshl_add_u64 v[2:3], s[60:61], 0, v[2:3]
	s_lshl_b32 s54, s4, 1
	v_mul_f32_e32 v4, v48, v0
	v_mul_f32_e32 v6, v32, v0
	v_mul_f32_e32 v5, v49, v0
	v_mul_f32_e32 v7, v33, v0
	v_mul_f32_e32 v8, v50, v0
	v_mul_f32_e32 v9, v34, v0
	v_mul_f32_e32 v10, v51, v0
	v_mul_f32_e32 v11, v35, v0
	v_mul_f32_e32 v12, v52, v0
	v_mul_f32_e32 v13, v36, v0
	v_mul_f32_e32 v14, v53, v0
	v_mul_f32_e32 v15, v37, v0
	v_mul_f32_e32 v16, v54, v0
	v_mul_f32_e32 v17, v38, v0
	v_mul_f32_e32 v18, v55, v0
	v_mul_f32_e32 v19, v39, v0
	v_mul_f32_e32 v20, v56, v0
	v_mul_f32_e32 v21, v40, v0
	v_mul_f32_e32 v22, v57, v0
	v_mul_f32_e32 v23, v41, v0
	v_mul_f32_e32 v24, v58, v0
	v_mul_f32_e32 v25, v42, v0
	v_mul_f32_e32 v26, v59, v0
	v_mul_f32_e32 v27, v43, v0
	v_mul_f32_e32 v28, v60, v0
	v_mul_f32_e32 v29, v44, v0
	v_mul_f32_e32 v30, v61, v0
	v_mul_f32_e32 v31, v45, v0
	v_mul_f32_e32 v32, v62, v0
	v_mul_f32_e32 v33, v46, v0
	v_mul_f32_e32 v34, v63, v0
	v_mul_f32_e32 v35, v47, v0
	v_lshl_add_u64 v[2:3], v[2:3], 0, s[54:55]
	v_lshlrev_b32_e32 v0, 2, v179
	v_lshl_add_u64 v[2:3], v[2:3], 0, v[0:1]
	s_mov_b64 s[0:1], 0
	v_cvt_pk_bf16_f32 v36, v4, v5
	v_cvt_pk_bf16_f32 v37, v8, v10
	v_cvt_pk_bf16_f32 v38, v12, v14
	v_cvt_pk_bf16_f32 v39, v16, v18
	s_nop 1
	v_permlane32_swap_b32_e32 v36, v38
	v_permlane32_swap_b32_e32 v37, v39
	global_store_dwordx4 v[2:3], v[36:39], off
	v_cvt_pk_bf16_f32 v40, v6, v7
	v_cvt_pk_bf16_f32 v41, v9, v11
	v_cvt_pk_bf16_f32 v42, v13, v15
	v_cvt_pk_bf16_f32 v43, v17, v19
	s_nop 1
	v_permlane32_swap_b32_e32 v40, v42
	v_permlane32_swap_b32_e32 v41, v43
	global_store_dwordx4 v[2:3], v[40:43], off offset:64
	v_cvt_pk_bf16_f32 v44, v20, v22
	v_cvt_pk_bf16_f32 v45, v24, v26
	v_cvt_pk_bf16_f32 v46, v28, v30
	v_cvt_pk_bf16_f32 v47, v32, v34
	s_nop 1
	v_permlane32_swap_b32_e32 v44, v46
	v_permlane32_swap_b32_e32 v45, v47
	global_store_dwordx4 v[2:3], v[44:47], off offset:32
	v_cvt_pk_bf16_f32 v48, v21, v23
	v_cvt_pk_bf16_f32 v49, v25, v27
	v_cvt_pk_bf16_f32 v50, v29, v31
	v_cvt_pk_bf16_f32 v51, v33, v35
	s_nop 1
	v_permlane32_swap_b32_e32 v48, v50
	v_permlane32_swap_b32_e32 v49, v51
	global_store_dwordx4 v[2:3], v[48:51], off offset:96
	s_barrier
